# attention: wave 0 touches the next work item's first K/V key tiles (cache warm-up) during the last tile iteration
# baseline (speedup 1.0000x reference)
; __device__ __forceinline__ void item_attn(const Params& p, int l, int aidx) {
;     ...
;     int qb = 7 - (aidx >> 8); int r = aidx & 255; b = r >> 3; hd = r & 7;
;     nq = 256; qpos0 = qb * 256; tokq0 = (long)b * 2048 + qpos0; ntiles = qb * 4 + 4;
;     kbase = p.out + OFF_KP + ((long)l * 65536 + (long)b * 2048) * 512 + hd * 64;
;     vbase = p.out + OFF_VP + ((long)l * 65536 + (long)b * 2048) * 512 + hd * 64;
.Lattn_touch:
	v_readlane_b32 s100, v247, 13
	v_readlane_b32 s101, v247, 14
	s_add_i32 s99, s47, -1
	s_add_u32 s100, s100, s44
	s_addc_u32 s101, s101, s45
	v_min_i32_e32 v236, s99, v84
	v_min_i32_e32 v238, s99, v86
	v_ashrrev_i32_e32 v237, 31, v236
	v_ashrrev_i32_e32 v239, 31, v238
	v_lshl_add_u64 v[236:237], s[34:35], 0, v[236:237]
	v_lshl_add_u64 v[238:239], s[34:35], 0, v[238:239]
	v_lshlrev_b64 v[236:237], 10, v[236:237]
	v_lshlrev_b64 v[238:239], 10, v[238:239]
	v_lshl_add_u64 v[236:237], s[100:101], 0, v[236:237]
	v_lshl_add_u64 v[238:239], s[100:101], 0, v[238:239]
	global_load_dword v234, v[236:237], off
	global_load_dword v235, v[238:239], off
	s_cmp_lg_u32 s98, 0
	s_cbranch_scc0 .Lkv_skip
	v_readfirstlane_b32 s99, v188
	s_cmp_lt_u32 s99, 64
	s_cbranch_scc0 .Lkv_skip
	v_readfirstlane_b32 s99, v245
	s_sub_u32 s99, s99, 0x14a
	s_cmp_lt_u32 s99, 0x800
	s_cbranch_scc0 .Lkv_skip
	s_bfe_u32 s100, s99, 0x50003
	s_lshl_b32 s100, s100, 22
	s_lshr_b32 s101, s99, 8
	s_sub_i32 s101, 7, s101
	s_lshl_b32 s101, s101, 19
	s_add_i32 s100, s100, s101
	s_and_b32 s101, s99, 7
	s_lshl_b32 s101, s101, 8
	s_add_i32 s100, s100, s101
	s_add_i32 s100, s100, 0x40000
	v_readlane_b32 s99, v246, 17
	v_lshrrev_b32_e32 v236, 1, v215
	v_and_b32_e32 v237, 1, v215
	v_lshlrev_b32_e32 v236, 11, v236
	v_lshl_or_b32 v236, v237, 7, v236
	s_lshl_b32 s99, s99, 2
	s_add_u32 s100, s100, s99
	v_add_u32_e32 v236, s100, v236
	v_add_u32_e32 v237, 0x10000, v236
	v_add_u32_e32 v238, 0x20000, v236
	v_add_u32_e32 v239, 0x30000, v236
	v_readlane_b32 s100, v248, 8
	v_readlane_b32 s101, v248, 9
	s_nop 4
	global_load_dword v240, v236, s[100:101]
	global_load_dword v241, v237, s[100:101]
	global_load_dword v242, v238, s[100:101]
	global_load_dword v243, v239, s[100:101]
	v_readlane_b32 s100, v248, 6
	v_readlane_b32 s101, v248, 7
	s_nop 4
	global_load_dword v240, v236, s[100:101]
	global_load_dword v241, v237, s[100:101]
	global_load_dword v242, v238, s[100:101]
	global_load_dword v243, v239, s[100:101]
